# phase_prep part 1 (LoRA A operand) hand-written: both task rounds of a tile with all loads in flight, branch-free tanh/identity/sigmoid select
# speedup vs baseline: 1.0103x; 1.0064x over previous
; DI unsigned pack2(float a, float b) { unsigned r; asm volatile("v_cvt_pk_bf16_f32 %0, %1, %2" : "=v"(r) : "v"(a), "v"(b)); return r; }
; DN void phase_prep(const Params& p, int l, char* smem) {
;     ...
;     for (int i = tid; i < 8 * 48; i += 256) {
;       const int tk = i / 48, g8 = i - tk * 48, cc = g8 * 8;
;       const int m = m0 + tk, t = m % TT;
;       const bfr* row = P + (size_t)m * PW + 768 + cc;
;       const bool hp = (t != 0 && t != TL), hn = (t != TL - 1 && t != TT - 1);
;       const u32x4 cur = *(const u32x4*)row;
;       u32x4 prv = {0u, 0u, 0u, 0u}, nxt = {0u, 0u, 0u, 0u};
;       if (hp) prv = *(const u32x4*)(row - PW);
;       if (hn) nxt = *(const u32x4*)(row + PW);
;       const f32x4v ma0 = *(const f32x4v*)(mu + 768 + cc), ma1 = *(const f32x4v*)(mu + 768 + cc + 4);
;       const f32x4v mb0 = *(const f32x4v*)(mu + 1152 + 768 + cc), mb1 = *(const f32x4v*)(mu + 1152 + 768 + cc + 4);
;       const float m0v[8] = {ma0.x, ma0.y, ma0.z, ma0.w, ma1.x, ma1.y, ma1.z, ma1.w};
;       const float m1v[8] = {mb0.x, mb0.y, mb0.z, mb0.w, mb1.x, mb1.y, mb1.z, mb1.w};
;       const unsigned cw_[4] = {cur.x, cur.y, cur.z, cur.w}, pw_[4] = {prv.x, prv.y, prv.z, prv.w}, nw_[4] = {nxt.x, nxt.y, nxt.z, nxt.w};
;       float val[8];
; #pragma unroll
;       for (int e = 0; e < 8; ++e) {
;         const float x = (e & 1) ? __uint_as_float(cw_[e >> 1] & 0xffff0000u) : __uint_as_float(cw_[e >> 1] << 16);
;         const float xp = (e & 1) ? __uint_as_float(pw_[e >> 1] & 0xffff0000u) : __uint_as_float(pw_[e >> 1] << 16);
;         const float xn = (e & 1) ? __uint_as_float(nw_[e >> 1] & 0xffff0000u) : __uint_as_float(nw_[e >> 1] << 16);
;         const float xs = x + m0v[e] * (xp - x) + m1v[e] * (xn - x);
;         val[e] = (cc < 128) ? (1.f - 2.f * __builtin_amdgcn_rcpf(1.f + __expf(2.f * xs))) : ((cc < 256) ? xs : __builtin_amdgcn_rcpf(1.f + __expf(-xs)));
;       }
;       u32x4 ow; ow.x = pack2(val[0], val[1]); ow.y = pack2(val[2], val[3]); ow.z = pack2(val[4], val[5]); ow.w = pack2(val[6], val[7]);
;       *(u32x4*)(AL + (size_t)m * 384 + cc) = ow;
.LBB0_268:
	s_lshl_b32 s24, s20, 3
	s_and_saveexec_b64 s[8:9], s[2:3]
	s_cbranch_execz .LBB0_309
	s_mov_b64 s[10:11], exec
	v_readlane_b32 s6, v252, 62
	v_readlane_b32 s7, v252, 63
	s_mul_hi_u32 s98, s24, 0x38e38e39
	s_lshr_b32 s98, s98, 9
	s_mulk_i32 s98, 0x900
	s_sub_u32 s98, s24, s98
	v_mov_b32_e32 v0, v183
	v_mul_u32_u24_e32 v16, 0x556, v0
	v_lshrrev_b32_e32 v2, 16, v16
	v_mul_u32_u24_e32 v16, 48, v2
	v_sub_u32_e32 v4, v0, v16
	v_add_u32_e32 v6, s24, v2
	v_lshlrev_b32_e32 v16, 4, v4
	v_mad_u32_u24 v8, v6, s88, v16
	v_lshlrev_b32_e32 v12, 5, v4
	v_mov_b32_e32 v17, 0x300
	v_mad_u32_u24 v14, v6, v17, v16
	v_add_u32_e32 v1, 0x100, v183
	v_mul_u32_u24_e32 v16, 0x556, v1
	v_lshrrev_b32_e32 v3, 16, v16
	v_mul_u32_u24_e32 v16, 48, v3
	v_sub_u32_e32 v5, v1, v16
	v_add_u32_e32 v7, s24, v3
	v_lshlrev_b32_e32 v16, 4, v5
	v_mad_u32_u24 v9, v7, s88, v16
	v_lshlrev_b32_e32 v13, 5, v5
	v_mov_b32_e32 v17, 0x300
	v_mad_u32_u24 v15, v7, v17, v16
	v_add_u32_e32 v10, 0xffffe680, v8
	v_add_u32_e32 v16, 0x1980, v8
	v_add_u32_e32 v17, 0xffffe680, v9
	v_add_u32_e32 v11, 0x1980, v9
	v_mov_b32_e32 v36, 0
	v_mov_b32_e32 v100, 0
	v_mov_b32_e32 v37, 0
	v_mov_b32_e32 v101, 0
	v_mov_b32_e32 v38, 0
	v_mov_b32_e32 v102, 0
	v_mov_b32_e32 v39, 0
	v_mov_b32_e32 v103, 0
	v_cmp_gt_u32_e32 vcc, 0x80, v183
	s_and_b64 s[16:17], s[10:11], vcc
	global_load_dwordx4 v[32:35], v8, s[84:85] offset:1536
	v_cmp_ne_u32_e32 vcc, 0, v2
	s_andn2_b32 s99, s98, 0x800
	s_cselect_b64 vcc, s[10:11], vcc
	s_and_b64 exec, s[10:11], vcc
	global_load_dwordx4 v[36:39], v10, s[84:85] offset:1536
	s_mov_b64 exec, s[10:11]
	global_load_dwordx4 v[40:43], v16, s[84:85] offset:1536
	global_load_dwordx4 v[44:47], v12, s[12:13] offset:3072
	global_load_dwordx4 v[48:51], v12, s[12:13] offset:3088
	global_load_dwordx4 v[52:55], v12, s[14:15]
	global_load_dwordx4 v[56:59], v12, s[14:15] offset:16
	s_mov_b64 exec, s[16:17]
	global_load_dwordx4 v[92:95], v9, s[84:85] offset:1536
	global_load_dwordx4 v[96:99], v17, s[84:85] offset:1536
	v_cmp_ne_u32_e32 vcc, 7, v3
	s_sub_u32 s99, s98, 0x7f8
	s_andn2_b32 s99, s99, 0x100
	s_cselect_b64 vcc, s[10:11], vcc
	s_and_b64 exec, s[16:17], vcc
	global_load_dwordx4 v[100:103], v11, s[84:85] offset:1536
	s_mov_b64 exec, s[16:17]
	global_load_dwordx4 v[104:107], v13, s[12:13] offset:3072
	global_load_dwordx4 v[108:111], v13, s[12:13] offset:3088
	global_load_dwordx4 v[112:115], v13, s[14:15]
	global_load_dwordx4 v[116:119], v13, s[14:15] offset:16
	s_mov_b64 exec, s[10:11]
	s_waitcnt vmcnt(7)
	v_cmp_gt_u32_e32 vcc, 16, v4
	v_mov_b32_e32 v86, 0xbf800000
	v_mov_b32_e32 v84, 2.0
	v_cndmask_b32_e32 v86, v86, v84, vcc
	v_lshlrev_b32_e32 v60, 16, v32
	v_lshlrev_b32_e32 v84, 16, v36
	v_lshlrev_b32_e32 v85, 16, v40
	v_sub_f32_e32 v84, v84, v60
	v_sub_f32_e32 v85, v85, v60
	v_fmac_f32_e32 v60, v84, v44
	v_fmac_f32_e32 v60, v52, v85
	v_mul_f32_e32 v68, 0x3fb8aa3b, v60
	v_mul_f32_e32 v68, v68, v86
	v_exp_f32_e32 v68, v68
	v_and_b32_e32 v61, 0xffff0000, v32
	v_and_b32_e32 v84, 0xffff0000, v36
	v_and_b32_e32 v85, 0xffff0000, v40
	v_sub_f32_e32 v84, v84, v61
	v_sub_f32_e32 v85, v85, v61
	v_fmac_f32_e32 v61, v84, v45
	v_fmac_f32_e32 v61, v53, v85
	v_mul_f32_e32 v69, 0x3fb8aa3b, v61
	v_mul_f32_e32 v69, v69, v86
	v_exp_f32_e32 v69, v69
	v_lshlrev_b32_e32 v62, 16, v33
	v_lshlrev_b32_e32 v84, 16, v37
	v_lshlrev_b32_e32 v85, 16, v41
	v_sub_f32_e32 v84, v84, v62
	v_sub_f32_e32 v85, v85, v62
	v_fmac_f32_e32 v62, v84, v46
	v_fmac_f32_e32 v62, v54, v85
	v_mul_f32_e32 v70, 0x3fb8aa3b, v62
	v_mul_f32_e32 v70, v70, v86
	v_exp_f32_e32 v70, v70
	v_and_b32_e32 v63, 0xffff0000, v33
	v_and_b32_e32 v84, 0xffff0000, v37
	v_and_b32_e32 v85, 0xffff0000, v41
	v_sub_f32_e32 v84, v84, v63
	v_sub_f32_e32 v85, v85, v63
	v_fmac_f32_e32 v63, v84, v47
	v_fmac_f32_e32 v63, v55, v85
	v_mul_f32_e32 v71, 0x3fb8aa3b, v63
	v_mul_f32_e32 v71, v71, v86
	v_exp_f32_e32 v71, v71
	v_lshlrev_b32_e32 v64, 16, v34
	v_lshlrev_b32_e32 v84, 16, v38
	v_lshlrev_b32_e32 v85, 16, v42
	v_sub_f32_e32 v84, v84, v64
	v_sub_f32_e32 v85, v85, v64
	v_fmac_f32_e32 v64, v84, v48
	v_fmac_f32_e32 v64, v56, v85
	v_mul_f32_e32 v72, 0x3fb8aa3b, v64
	v_mul_f32_e32 v72, v72, v86
	v_exp_f32_e32 v72, v72
	v_and_b32_e32 v65, 0xffff0000, v34
	v_and_b32_e32 v84, 0xffff0000, v38
	v_and_b32_e32 v85, 0xffff0000, v42
	v_sub_f32_e32 v84, v84, v65
	v_sub_f32_e32 v85, v85, v65
	v_fmac_f32_e32 v65, v84, v49
	v_fmac_f32_e32 v65, v57, v85
	v_mul_f32_e32 v73, 0x3fb8aa3b, v65
	v_mul_f32_e32 v73, v73, v86
	v_exp_f32_e32 v73, v73
	v_lshlrev_b32_e32 v66, 16, v35
	v_lshlrev_b32_e32 v84, 16, v39
	v_lshlrev_b32_e32 v85, 16, v43
	v_sub_f32_e32 v84, v84, v66
	v_sub_f32_e32 v85, v85, v66
	v_fmac_f32_e32 v66, v84, v50
	v_fmac_f32_e32 v66, v58, v85
	v_mul_f32_e32 v74, 0x3fb8aa3b, v66
	v_mul_f32_e32 v74, v74, v86
	v_exp_f32_e32 v74, v74
	v_and_b32_e32 v67, 0xffff0000, v35
	v_and_b32_e32 v84, 0xffff0000, v39
	v_and_b32_e32 v85, 0xffff0000, v43
	v_sub_f32_e32 v84, v84, v67
	v_sub_f32_e32 v85, v85, v67
	v_fmac_f32_e32 v67, v84, v51
	v_fmac_f32_e32 v67, v59, v85
	v_mul_f32_e32 v75, 0x3fb8aa3b, v67
	v_mul_f32_e32 v75, v75, v86
	v_exp_f32_e32 v75, v75
	v_add_f32_e32 v68, 1.0, v68
	v_add_f32_e32 v69, 1.0, v69
	v_add_f32_e32 v70, 1.0, v70
	v_add_f32_e32 v71, 1.0, v71
	v_add_f32_e32 v72, 1.0, v72
	v_add_f32_e32 v73, 1.0, v73
	v_add_f32_e32 v74, 1.0, v74
	v_add_f32_e32 v75, 1.0, v75
	v_rcp_f32_e32 v68, v68
	v_rcp_f32_e32 v69, v69
	v_rcp_f32_e32 v70, v70
	v_rcp_f32_e32 v71, v71
	v_rcp_f32_e32 v72, v72
	v_rcp_f32_e32 v73, v73
	v_rcp_f32_e32 v74, v74
	v_rcp_f32_e32 v75, v75
	v_fma_f32 v76, v68, -2.0, 1.0
	v_fma_f32 v77, v69, -2.0, 1.0
	v_fma_f32 v78, v70, -2.0, 1.0
	v_fma_f32 v79, v71, -2.0, 1.0
	v_fma_f32 v80, v72, -2.0, 1.0
	v_fma_f32 v81, v73, -2.0, 1.0
	v_fma_f32 v82, v74, -2.0, 1.0
	v_fma_f32 v83, v75, -2.0, 1.0
	v_cmp_gt_u32_e32 vcc, 32, v4
	s_nop 1
	v_cndmask_b32_e32 v68, v68, v60, vcc
	v_cndmask_b32_e32 v69, v69, v61, vcc
	v_cndmask_b32_e32 v70, v70, v62, vcc
	v_cndmask_b32_e32 v71, v71, v63, vcc
	v_cndmask_b32_e32 v72, v72, v64, vcc
	v_cndmask_b32_e32 v73, v73, v65, vcc
	v_cndmask_b32_e32 v74, v74, v66, vcc
	v_cndmask_b32_e32 v75, v75, v67, vcc
	v_cmp_gt_u32_e32 vcc, 16, v4
	s_nop 1
	v_cndmask_b32_e32 v68, v68, v76, vcc
	v_cndmask_b32_e32 v69, v69, v77, vcc
	v_cndmask_b32_e32 v70, v70, v78, vcc
	v_cndmask_b32_e32 v71, v71, v79, vcc
	v_cndmask_b32_e32 v72, v72, v80, vcc
	v_cndmask_b32_e32 v73, v73, v81, vcc
	v_cndmask_b32_e32 v74, v74, v82, vcc
	v_cndmask_b32_e32 v75, v75, v83, vcc
	v_cvt_pk_bf16_f32 v32, v68, v69
	v_cvt_pk_bf16_f32 v33, v70, v71
	v_cvt_pk_bf16_f32 v34, v72, v73
	v_cvt_pk_bf16_f32 v35, v74, v75
	global_store_dwordx4 v14, v[32:35], s[6:7]
	s_mov_b64 exec, s[16:17]
	s_cbranch_execz .Lprep1_done
; DI unsigned pack2(float a, float b) { unsigned r; asm volatile("v_cvt_pk_bf16_f32 %0, %1, %2" : "=v"(r) : "v"(a), "v"(b)); return r; }
; DN void phase_prep(const Params& p, int l, char* smem) {
;     ...
;     for (int i = tid; i < 8 * 48; i += 256) {
;       const int tk = i / 48, g8 = i - tk * 48, cc = g8 * 8;
;       const int m = m0 + tk, t = m % TT;
;       const bfr* row = P + (size_t)m * PW + 768 + cc;
;       const bool hp = (t != 0 && t != TL), hn = (t != TL - 1 && t != TT - 1);
;       const u32x4 cur = *(const u32x4*)row;
;       u32x4 prv = {0u, 0u, 0u, 0u}, nxt = {0u, 0u, 0u, 0u};
;       if (hp) prv = *(const u32x4*)(row - PW);
;       if (hn) nxt = *(const u32x4*)(row + PW);
;       const f32x4v ma0 = *(const f32x4v*)(mu + 768 + cc), ma1 = *(const f32x4v*)(mu + 768 + cc + 4);
;       const f32x4v mb0 = *(const f32x4v*)(mu + 1152 + 768 + cc), mb1 = *(const f32x4v*)(mu + 1152 + 768 + cc + 4);
;       const float m0v[8] = {ma0.x, ma0.y, ma0.z, ma0.w, ma1.x, ma1.y, ma1.z, ma1.w};
;       const float m1v[8] = {mb0.x, mb0.y, mb0.z, mb0.w, mb1.x, mb1.y, mb1.z, mb1.w};
;       const unsigned cw_[4] = {cur.x, cur.y, cur.z, cur.w}, pw_[4] = {prv.x, prv.y, prv.z, prv.w}, nw_[4] = {nxt.x, nxt.y, nxt.z, nxt.w};
;       float val[8];
; #pragma unroll
;       for (int e = 0; e < 8; ++e) {
;         const float x = (e & 1) ? __uint_as_float(cw_[e >> 1] & 0xffff0000u) : __uint_as_float(cw_[e >> 1] << 16);
;         const float xp = (e & 1) ? __uint_as_float(pw_[e >> 1] & 0xffff0000u) : __uint_as_float(pw_[e >> 1] << 16);
;         const float xn = (e & 1) ? __uint_as_float(nw_[e >> 1] & 0xffff0000u) : __uint_as_float(nw_[e >> 1] << 16);
;         const float xs = x + m0v[e] * (xp - x) + m1v[e] * (xn - x);
;         val[e] = (cc < 128) ? (1.f - 2.f * __builtin_amdgcn_rcpf(1.f + __expf(2.f * xs))) : ((cc < 256) ? xs : __builtin_amdgcn_rcpf(1.f + __expf(-xs)));
;       }
;       u32x4 ow; ow.x = pack2(val[0], val[1]); ow.y = pack2(val[2], val[3]); ow.z = pack2(val[4], val[5]); ow.w = pack2(val[6], val[7]);
;       *(u32x4*)(AL + (size_t)m * 384 + cc) = ow;
	s_waitcnt vmcnt(1)
	v_cmp_gt_u32_e32 vcc, 16, v5
	v_mov_b32_e32 v146, 0xbf800000
	v_mov_b32_e32 v144, 2.0
	v_cndmask_b32_e32 v146, v146, v144, vcc
	v_lshlrev_b32_e32 v120, 16, v92
	v_lshlrev_b32_e32 v144, 16, v96
	v_lshlrev_b32_e32 v145, 16, v100
	v_sub_f32_e32 v144, v144, v120
	v_sub_f32_e32 v145, v145, v120
	v_fmac_f32_e32 v120, v144, v104
	v_fmac_f32_e32 v120, v112, v145
	v_mul_f32_e32 v128, 0x3fb8aa3b, v120
	v_mul_f32_e32 v128, v128, v146
	v_exp_f32_e32 v128, v128
	v_and_b32_e32 v121, 0xffff0000, v92
	v_and_b32_e32 v144, 0xffff0000, v96
	v_and_b32_e32 v145, 0xffff0000, v100
	v_sub_f32_e32 v144, v144, v121
	v_sub_f32_e32 v145, v145, v121
	v_fmac_f32_e32 v121, v144, v105
	v_fmac_f32_e32 v121, v113, v145
	v_mul_f32_e32 v129, 0x3fb8aa3b, v121
	v_mul_f32_e32 v129, v129, v146
	v_exp_f32_e32 v129, v129
	v_lshlrev_b32_e32 v122, 16, v93
	v_lshlrev_b32_e32 v144, 16, v97
	v_lshlrev_b32_e32 v145, 16, v101
	v_sub_f32_e32 v144, v144, v122
	v_sub_f32_e32 v145, v145, v122
	v_fmac_f32_e32 v122, v144, v106
	v_fmac_f32_e32 v122, v114, v145
	v_mul_f32_e32 v130, 0x3fb8aa3b, v122
	v_mul_f32_e32 v130, v130, v146
	v_exp_f32_e32 v130, v130
	v_and_b32_e32 v123, 0xffff0000, v93
	v_and_b32_e32 v144, 0xffff0000, v97
	v_and_b32_e32 v145, 0xffff0000, v101
	v_sub_f32_e32 v144, v144, v123
	v_sub_f32_e32 v145, v145, v123
	v_fmac_f32_e32 v123, v144, v107
	v_fmac_f32_e32 v123, v115, v145
	v_mul_f32_e32 v131, 0x3fb8aa3b, v123
	v_mul_f32_e32 v131, v131, v146
	v_exp_f32_e32 v131, v131
	v_lshlrev_b32_e32 v124, 16, v94
	v_lshlrev_b32_e32 v144, 16, v98
	v_lshlrev_b32_e32 v145, 16, v102
	v_sub_f32_e32 v144, v144, v124
	v_sub_f32_e32 v145, v145, v124
	v_fmac_f32_e32 v124, v144, v108
	v_fmac_f32_e32 v124, v116, v145
	v_mul_f32_e32 v132, 0x3fb8aa3b, v124
	v_mul_f32_e32 v132, v132, v146
	v_exp_f32_e32 v132, v132
	v_and_b32_e32 v125, 0xffff0000, v94
	v_and_b32_e32 v144, 0xffff0000, v98
	v_and_b32_e32 v145, 0xffff0000, v102
	v_sub_f32_e32 v144, v144, v125
	v_sub_f32_e32 v145, v145, v125
	v_fmac_f32_e32 v125, v144, v109
	v_fmac_f32_e32 v125, v117, v145
	v_mul_f32_e32 v133, 0x3fb8aa3b, v125
	v_mul_f32_e32 v133, v133, v146
	v_exp_f32_e32 v133, v133
	v_lshlrev_b32_e32 v126, 16, v95
	v_lshlrev_b32_e32 v144, 16, v99
	v_lshlrev_b32_e32 v145, 16, v103
	v_sub_f32_e32 v144, v144, v126
	v_sub_f32_e32 v145, v145, v126
	v_fmac_f32_e32 v126, v144, v110
	v_fmac_f32_e32 v126, v118, v145
	v_mul_f32_e32 v134, 0x3fb8aa3b, v126
	v_mul_f32_e32 v134, v134, v146
	v_exp_f32_e32 v134, v134
	v_and_b32_e32 v127, 0xffff0000, v95
	v_and_b32_e32 v144, 0xffff0000, v99
	v_and_b32_e32 v145, 0xffff0000, v103
	v_sub_f32_e32 v144, v144, v127
	v_sub_f32_e32 v145, v145, v127
	v_fmac_f32_e32 v127, v144, v111
	v_fmac_f32_e32 v127, v119, v145
	v_mul_f32_e32 v135, 0x3fb8aa3b, v127
	v_mul_f32_e32 v135, v135, v146
	v_exp_f32_e32 v135, v135
	v_add_f32_e32 v128, 1.0, v128
	v_add_f32_e32 v129, 1.0, v129
	v_add_f32_e32 v130, 1.0, v130
	v_add_f32_e32 v131, 1.0, v131
	v_add_f32_e32 v132, 1.0, v132
	v_add_f32_e32 v133, 1.0, v133
	v_add_f32_e32 v134, 1.0, v134
	v_add_f32_e32 v135, 1.0, v135
	v_rcp_f32_e32 v128, v128
	v_rcp_f32_e32 v129, v129
	v_rcp_f32_e32 v130, v130
	v_rcp_f32_e32 v131, v131
	v_rcp_f32_e32 v132, v132
	v_rcp_f32_e32 v133, v133
	v_rcp_f32_e32 v134, v134
	v_rcp_f32_e32 v135, v135
	v_fma_f32 v136, v128, -2.0, 1.0
	v_fma_f32 v137, v129, -2.0, 1.0
	v_fma_f32 v138, v130, -2.0, 1.0
	v_fma_f32 v139, v131, -2.0, 1.0
	v_fma_f32 v140, v132, -2.0, 1.0
	v_fma_f32 v141, v133, -2.0, 1.0
	v_fma_f32 v142, v134, -2.0, 1.0
	v_fma_f32 v143, v135, -2.0, 1.0
	v_cmp_gt_u32_e32 vcc, 32, v5
	s_nop 1
	v_cndmask_b32_e32 v128, v128, v120, vcc
	v_cndmask_b32_e32 v129, v129, v121, vcc
	v_cndmask_b32_e32 v130, v130, v122, vcc
	v_cndmask_b32_e32 v131, v131, v123, vcc
	v_cndmask_b32_e32 v132, v132, v124, vcc
	v_cndmask_b32_e32 v133, v133, v125, vcc
	v_cndmask_b32_e32 v134, v134, v126, vcc
	v_cndmask_b32_e32 v135, v135, v127, vcc
	v_cmp_gt_u32_e32 vcc, 16, v5
	s_nop 1
	v_cndmask_b32_e32 v128, v128, v136, vcc
	v_cndmask_b32_e32 v129, v129, v137, vcc
	v_cndmask_b32_e32 v130, v130, v138, vcc
	v_cndmask_b32_e32 v131, v131, v139, vcc
	v_cndmask_b32_e32 v132, v132, v140, vcc
	v_cndmask_b32_e32 v133, v133, v141, vcc
	v_cndmask_b32_e32 v134, v134, v142, vcc
	v_cndmask_b32_e32 v135, v135, v143, vcc
	v_cvt_pk_bf16_f32 v92, v128, v129
	v_cvt_pk_bf16_f32 v93, v130, v131
	v_cvt_pk_bf16_f32 v94, v132, v133
	v_cvt_pk_bf16_f32 v95, v134, v135
	global_store_dwordx4 v15, v[92:95], s[6:7]
.Lprep1_done:
	s_mov_b64 exec, s[10:11]
